# QKV/ConvIn epilogues: all eight rstd LDS reads issued at epilogue start into spare registers (later rows copy from them) so no row waits on an LDS read
# baseline (speedup 1.0000x reference)
; #define PG8_LAS __attribute__((address_space(3)))
; template <class Epi, class Sched, bool ALIGN_EPI = false, bool SP2 = false>
; __device__ __forceinline__ void gemm_phase(PG8_LAS unsigned char* lds, const Gemm g, const Sched& S, const Epi& E) {
;     ...
;         if constexpr (Epi::RSTD) {
;             const int slot = cur.pm == pmc0 ? 0 : cur.pm == pmc1 ? 1 : cur.pm == pmc2 ? 2 : cur.pm == pmc3 ? 3 : -1;
;             E(acc, cur, wr, wc, fr, fq, slot >= 0 ? (const PG8_LAS float*)(lds + STAGE_BYTES) + slot * 256 : (const PG8_LAS float*)nullptr);
;     __device__ __forceinline__ void operator()(const f32x4 (&acc)[2][2][4][2], const Unit& u, int wr, int wc, int fr, int fq, const LAS float* rt) const {
;     ...
;                 const int row = row0 + ai * 128 + m * 16; const float rs = rt ? rt[wr * 64 + fr + ai * 128 + m * 16] : row_rstd(ssq, row);
.LBB0_174:
	s_cmp_gt_i32 s2, -1
	s_cselect_b64 s[50:51], -1, 0
	s_lshl_b32 s3, s2, 10
	s_add_i32 s3, s3, 0
	s_add_i32 s8, s3, 0x20000
	s_cmp_lt_i32 s2, 0
	s_cselect_b64 s[2:3], -1, 0
	s_and_b64 vcc, s[2:3], exec
	s_cselect_b32 s2, 0, s8
	s_lshl_b32 s3, s98, 2
	v_and_b32_e32 v158, 15, v160
	s_add_i32 s2, s2, s3
	v_lshl_add_u32 v162, v158, 2, s2
	s_mov_b64 s[28:29], -1
	s_cbranch_vccnz .LBB0_176
	ds_read_b32 v160, v162
	ds_read_b32 v200, v162 offset:64
	ds_read_b32 v201, v162 offset:128
	ds_read_b32 v202, v162 offset:192
	ds_read_b32 v203, v162 offset:512
	ds_read_b32 v204, v162 offset:576
	ds_read_b32 v205, v162 offset:640
	ds_read_b32 v206, v162 offset:704
	s_mov_b64 s[28:29], 0

;     __device__ __forceinline__ void operator()(const f32x4 (&acc)[2][2][4][2], const Unit& u, int wr, int wc, int fr, int fq, const LAS float* rt) const {
;     ...
;                 const int row = row0 + ai * 128 + m * 16; const float rs = rt ? rt[wr * 64 + fr + ai * 128 + m * 16] : row_rstd(ssq, row);
;                 f32x4 v[2][2]; float ss = 0.f;
; #pragma unroll
;                 for (int bj = 0; bj < 2; ++bj)
; #pragma unroll
;                     for (int n = 0; n < 2; ++n) { v[bj][n] = acc[ai][bj][m][n] * rs; const f32x4 q = v[bj][n] * v[bj][n]; ss += (q[0] + q[1]) + (q[2] + q[3]); }
;                 ss = sum_x16_x32(ss);
;                 const float sc = kind < 2 ? __builtin_amdgcn_rsqf(ss * (1.f / 64.f) + RMS_EPS) : 1.f;
;                 const int tt = row & (SEQ - 1); const int prow = (row & ~(SEQ - 1)) + (tt & ((1 << rsh) - 1)) * (SEQ >> rsh) + (tt >> rsh);
; #pragma unroll
;                 for (int bj = 0; bj < 2; ++bj)
;                     gst<u32x4>((kind == 0 ? Oq : Okv + (size_t)(kind - 1) * 16 * M * 64) + ((size_t)(4 * (u.pn & 3) + wc) * M + prow) * 64 + 32 * bj + 8 * fq, pack8(v[bj][0] * sc * gv[bj][0], v[bj][1] * sc * gv[bj][1]));
;             }
.LBB0_178:
	s_waitcnt lgkmcnt(0)
	v_pk_mul_f32 v[128:129], v[128:129], v[160:161] op_sel_hi:[1,0]
	v_pk_mul_f32 v[126:127], v[126:127], v[160:161] op_sel_hi:[1,0]
	v_pk_mul_f32 v[164:165], v[128:129], v[128:129]
	v_pk_mul_f32 v[166:167], v[126:127], v[126:127]
	v_pk_mul_f32 v[120:121], v[120:121], v[160:161] op_sel_hi:[1,0]
	v_pk_mov_b32 v[168:169], v[166:167], v[164:165] op_sel:[1,0]
	v_mov_b32_e32 v167, v165
	v_pk_mul_f32 v[118:119], v[118:119], v[160:161] op_sel_hi:[1,0]
	v_pk_add_f32 v[164:165], v[168:169], v[166:167]
	v_pk_mul_f32 v[166:167], v[120:121], v[120:121]
	v_pk_mul_f32 v[168:169], v[118:119], v[118:119]
	v_pk_mul_f32 v[124:125], v[124:125], v[160:161] op_sel_hi:[1,0]
	v_pk_mov_b32 v[170:171], v[168:169], v[166:167] op_sel:[1,0]
	v_mov_b32_e32 v169, v167
	v_pk_add_f32 v[166:167], v[170:171], v[168:169]
	v_pk_mul_f32 v[122:123], v[122:123], v[160:161] op_sel_hi:[1,0]
	v_pk_mul_f32 v[172:173], v[116:117], v[160:161] op_sel_hi:[1,0]
	v_pk_mul_f32 v[174:175], v[114:115], v[160:161] op_sel_hi:[1,0]
	v_pk_add_f32 v[164:165], v[164:165], v[164:165] op_sel_hi:[0,1]
	v_pk_add_f32 v[166:167], v[166:167], v[166:167] op_sel_hi:[0,1]
	v_pk_mul_f32 v[168:169], v[124:125], v[124:125]
	v_pk_mul_f32 v[170:171], v[122:123], v[122:123]
	v_pk_mul_f32 v[114:115], v[172:173], v[172:173]
	v_pk_mul_f32 v[116:117], v[174:175], v[174:175]
	v_add_f32_e32 v171, v170, v171
	v_add_f32_e32 v169, v168, v169
	v_mov_b32_e32 v170, v116
	v_mov_b32_e32 v168, v117
	v_mov_b32_e32 v164, v114
	v_mov_b32_e32 v166, v115
	v_pk_add_f32 v[116:117], v[170:171], v[168:169]
	v_pk_add_f32 v[114:115], v[164:165], v[166:167]
	s_lshl_b32 s3, s4, 2
	v_pk_add_f32 v[114:115], v[116:117], v[114:115]
	s_and_b32 s3, s3, 12
	v_add_f32_e32 v114, v114, v115
	v_mov_b32_e32 v115, v114
	s_nop 1
	v_permlane16_swap_b32 v114, v115
	s_nop 1
	v_readlane_b32 s4, v255, 44
	v_add_f32_e32 v114, v114, v115
	v_mov_b32_e32 v115, v114
	s_nop 1
	v_permlane32_swap_b32 v114, v115
	s_nop 1
	s_or_b32 s3, s3, s4
	v_add_f32_e32 v114, v114, v115
	v_fmamk_f32 v114, v114, 0x3c800000, v251
	v_rsq_f32_e32 v114, v114
	s_ashr_i32 s25, s24, 31
	s_lshl_b32 s4, s3, 15
	s_lshl_b64 s[8:9], s[24:25], 26
	s_and_b32 s26, s2, 0xffffe000
	v_readlane_b32 s2, v255, 27
	v_readlane_b32 s3, v255, 28
	s_add_u32 s2, s2, s8
	v_cndmask_b32_e64 v160, 1.0, v114, s[42:43]
	v_and_b32_e32 v114, 0x1fcf, v158
	s_addc_u32 s3, s3, s9
	v_lshrrev_b32_e32 v114, s58, v114
	s_add_u32 s2, s2, 0xfc000000
	v_bitop3_b32 v115, v158, s99, v252 bitop3:0x80
	v_or_b32_e32 v114, s26, v114
	s_addc_u32 s3, s3, -1
	v_mad_u32_u24 v114, v115, s59, v114
	s_and_b64 s[0:1], s[0:1], exec
	v_ashrrev_i32_e32 v115, 31, v114
	v_readlane_b32 s0, v255, 25
	v_lshl_add_u64 v[114:115], v[114:115], 0, s[4:5]
	v_readlane_b32 s1, v255, 26
	v_lshlrev_b64 v[114:115], 7, v[114:115]
	s_cselect_b32 s1, s1, s3
	s_cselect_b32 s0, s0, s2
	v_lshl_add_u64 v[116:117], s[0:1], 0, v[114:115]
	v_lshlrev_b32_e32 v114, 1, v163
	v_mov_b32_e32 v115, v96
	v_lshl_add_u64 v[164:165], v[116:117], 0, v[114:115]
	v_pk_mul_f32 v[116:117], v[126:127], v[160:161] op_sel_hi:[1,0]
	v_pk_mul_f32 v[118:119], v[118:119], v[160:161] op_sel_hi:[1,0]
	v_pk_mul_f32 v[126:127], v[128:129], v[160:161] op_sel_hi:[1,0]
	v_pk_mul_f32 v[116:117], v[144:145], v[116:117]
	v_pk_mul_f32 v[120:121], v[120:121], v[160:161] op_sel_hi:[1,0]
	v_pk_mul_f32 v[118:119], v[142:143], v[118:119]
	v_pk_mul_f32 v[126:127], v[146:147], v[126:127]
	v_pk_mul_f32 v[120:121], v[148:149], v[120:121]
	v_cvt_pk_bf16_f32 v116, v116, v117
	v_cvt_pk_bf16_f32 v117, v126, v127
	v_cvt_pk_bf16_f32 v118, v118, v119
	v_cndmask_b32_e64 v115, 0, 1, s[50:51]
	v_cvt_pk_bf16_f32 v119, v120, v121
	global_store_dwordx4 v[164:165], v[116:119], off
	v_pk_mul_f32 v[120:121], v[174:175], v[160:161] op_sel_hi:[1,0]
	v_cmp_ne_u32_e64 s[44:45], 1, v115
	v_pk_mul_f32 v[116:117], v[122:123], v[160:161] op_sel_hi:[1,0]
	v_pk_mul_f32 v[118:119], v[124:125], v[160:161] op_sel_hi:[1,0]
	v_pk_mul_f32 v[116:117], v[152:153], v[116:117]
	v_pk_mul_f32 v[118:119], v[154:155], v[118:119]
	v_pk_mul_f32 v[122:123], v[172:173], v[160:161] op_sel_hi:[1,0]
	v_pk_mul_f32 v[120:121], v[150:151], v[120:121]
	v_cvt_pk_bf16_f32 v116, v116, v117
	v_cvt_pk_bf16_f32 v117, v118, v119
	s_andn2_b64 vcc, exec, s[50:51]
	v_cvt_pk_bf16_f32 v118, v120, v121
	s_mov_b64 s[24:25], -1
	v_pk_mul_f32 v[122:123], v[156:157], v[122:123]
	s_nop 0
	v_cvt_pk_bf16_f32 v119, v122, v123
	global_store_dwordx4 v[164:165], v[116:119], off offset:64
	s_cbranch_vccnz .LBB0_180
	s_nop 1
	v_mov_b32_e32 v118, v200
	s_mov_b64 s[24:25], 0

;     __device__ __forceinline__ void operator()(const f32x4 (&acc)[2][2][4][2], const Unit& u, int wr, int wc, int fr, int fq, const LAS float* rt) const {
;     ...
;                 const int row = row0 + ai * 128 + m * 16; const float rs = rt ? rt[wr * 64 + fr + ai * 128 + m * 16] : row_rstd(ssq, row);
;                 f32x4 v[2][2]; float ss = 0.f;
; #pragma unroll
;                 for (int bj = 0; bj < 2; ++bj)
; #pragma unroll
;                     for (int n = 0; n < 2; ++n) { v[bj][n] = acc[ai][bj][m][n] * rs; const f32x4 q = v[bj][n] * v[bj][n]; ss += (q[0] + q[1]) + (q[2] + q[3]); }
;                 ss = sum_x16_x32(ss);
;                 const float sc = kind < 2 ? __builtin_amdgcn_rsqf(ss * (1.f / 64.f) + RMS_EPS) : 1.f;
;                 const int tt = row & (SEQ - 1); const int prow = (row & ~(SEQ - 1)) + (tt & ((1 << rsh) - 1)) * (SEQ >> rsh) + (tt >> rsh);
; #pragma unroll
;                 for (int bj = 0; bj < 2; ++bj)
;                     gst<u32x4>((kind == 0 ? Oq : Okv + (size_t)(kind - 1) * 16 * M * 64) + ((size_t)(4 * (u.pn & 3) + wc) * M + prow) * 64 + 32 * bj + 8 * fq, pack8(v[bj][0] * sc * gv[bj][0], v[bj][1] * sc * gv[bj][1]));
;             }
.LBB0_182:
	s_waitcnt lgkmcnt(0)
	v_pk_mul_f32 v[112:113], v[112:113], v[118:119] op_sel_hi:[1,0]
	v_pk_mul_f32 v[110:111], v[110:111], v[118:119] op_sel_hi:[1,0]
	v_pk_mul_f32 v[120:121], v[112:113], v[112:113]
	v_pk_mul_f32 v[122:123], v[110:111], v[110:111]
	v_pk_mul_f32 v[104:105], v[104:105], v[118:119] op_sel_hi:[1,0]
	v_pk_mov_b32 v[124:125], v[122:123], v[120:121] op_sel:[1,0]
	v_mov_b32_e32 v123, v121
	v_pk_mul_f32 v[102:103], v[102:103], v[118:119] op_sel_hi:[1,0]
	v_pk_add_f32 v[120:121], v[124:125], v[122:123]
	v_pk_mul_f32 v[122:123], v[104:105], v[104:105]
	v_pk_mul_f32 v[124:125], v[102:103], v[102:103]
	v_pk_mul_f32 v[106:107], v[106:107], v[118:119] op_sel_hi:[1,0]
	v_pk_mov_b32 v[126:127], v[124:125], v[122:123] op_sel:[1,0]
	v_mov_b32_e32 v125, v123
	v_pk_add_f32 v[122:123], v[126:127], v[124:125]
	v_pk_mul_f32 v[126:127], v[106:107], v[106:107]
	v_pk_mul_f32 v[108:109], v[108:109], v[118:119] op_sel_hi:[1,0]
	v_add_f32_e32 v119, v126, v127
	v_pk_mul_f32 v[126:127], v[100:101], v[118:119] op_sel_hi:[1,0]
	v_pk_mul_f32 v[128:129], v[98:99], v[118:119] op_sel_hi:[1,0]
	v_pk_add_f32 v[120:121], v[120:121], v[120:121] op_sel_hi:[0,1]
	v_pk_add_f32 v[122:123], v[122:123], v[122:123] op_sel_hi:[0,1]
	v_pk_mul_f32 v[124:125], v[108:109], v[108:109]
	v_pk_mul_f32 v[98:99], v[126:127], v[126:127]
	v_pk_mul_f32 v[100:101], v[128:129], v[128:129]
	v_add_f32_e32 v125, v124, v125
	v_mov_b32_e32 v118, v100
	v_mov_b32_e32 v124, v101
	v_mov_b32_e32 v120, v98
	v_mov_b32_e32 v122, v99
	v_pk_add_f32 v[100:101], v[118:119], v[124:125]
	v_pk_add_f32 v[98:99], v[120:121], v[122:123]
	v_mov_b32_e32 v115, v96
	v_pk_add_f32 v[98:99], v[100:101], v[98:99]
	s_and_b64 vcc, exec, s[44:45]
	v_add_f32_e32 v98, v98, v99
	v_mov_b32_e32 v99, v98
	s_nop 1
	v_permlane16_swap_b32 v98, v99
	s_nop 1
	s_mov_b64 s[24:25], -1
	v_add_f32_e32 v98, v98, v99
	v_mov_b32_e32 v99, v98
	s_nop 1
	v_permlane32_swap_b32 v98, v99
	s_nop 1
	s_nop 0
	v_add_f32_e32 v98, v98, v99
	v_fmamk_f32 v98, v98, 0x3c800000, v251
	v_rsq_f32_e32 v98, v98
	v_mov_b32_e32 v99, 0x1fdf
	v_bitop3_b32 v99, v116, s99, v99 bitop3:0x80
	v_cndmask_b32_e64 v118, 1.0, v98, s[42:43]
	v_and_b32_e32 v98, 0x1fdf, v116
	v_lshrrev_b32_e32 v98, s58, v98
	v_or_b32_e32 v98, s26, v98
	v_mad_u32_u24 v98, v99, s59, v98
	v_ashrrev_i32_e32 v99, 31, v98
	v_lshl_add_u64 v[98:99], v[98:99], 0, s[4:5]
	v_lshlrev_b64 v[98:99], 7, v[98:99]
	v_lshl_add_u64 v[98:99], s[0:1], 0, v[98:99]
	v_lshl_add_u64 v[116:117], v[98:99], 0, v[114:115]
	v_pk_mul_f32 v[98:99], v[110:111], v[118:119] op_sel_hi:[1,0]
	v_pk_mul_f32 v[100:101], v[112:113], v[118:119] op_sel_hi:[1,0]
	v_pk_mul_f32 v[98:99], v[144:145], v[98:99]
	v_pk_mul_f32 v[100:101], v[146:147], v[100:101]
	v_pk_mul_f32 v[102:103], v[102:103], v[118:119] op_sel_hi:[1,0]
	v_pk_mul_f32 v[104:105], v[104:105], v[118:119] op_sel_hi:[1,0]
	v_pk_mul_f32 v[102:103], v[142:143], v[102:103]
	v_pk_mul_f32 v[104:105], v[148:149], v[104:105]
	v_cvt_pk_bf16_f32 v98, v98, v99
	v_cvt_pk_bf16_f32 v99, v100, v101
	v_cvt_pk_bf16_f32 v100, v102, v103
	v_pk_mul_f32 v[102:103], v[128:129], v[118:119] op_sel_hi:[1,0]
	v_cvt_pk_bf16_f32 v101, v104, v105
	global_store_dwordx4 v[116:117], v[98:101], off
	v_pk_mul_f32 v[104:105], v[126:127], v[118:119] op_sel_hi:[1,0]
	v_pk_mul_f32 v[102:103], v[150:151], v[102:103]
	v_pk_mul_f32 v[98:99], v[106:107], v[118:119] op_sel_hi:[1,0]
	v_pk_mul_f32 v[100:101], v[108:109], v[118:119] op_sel_hi:[1,0]
	v_pk_mul_f32 v[98:99], v[152:153], v[98:99]
	v_pk_mul_f32 v[100:101], v[154:155], v[100:101]
	v_cvt_pk_bf16_f32 v98, v98, v99
	v_pk_mul_f32 v[104:105], v[156:157], v[104:105]
	v_cvt_pk_bf16_f32 v99, v100, v101
	v_cvt_pk_bf16_f32 v100, v102, v103
	s_nop 0
	v_cvt_pk_bf16_f32 v101, v104, v105
	global_store_dwordx4 v[116:117], v[98:101], off offset:64
	s_cbranch_vccnz .LBB0_184
	s_nop 1
	v_mov_b32_e32 v100, v201
	s_mov_b64 s[24:25], 0

;     __device__ __forceinline__ void operator()(const f32x4 (&acc)[2][2][4][2], const Unit& u, int wr, int wc, int fr, int fq, const LAS float* rt) const {
;     ...
;                 const int row = row0 + ai * 128 + m * 16; const float rs = rt ? rt[wr * 64 + fr + ai * 128 + m * 16] : row_rstd(ssq, row);
;                 f32x4 v[2][2]; float ss = 0.f;
; #pragma unroll
;                 for (int bj = 0; bj < 2; ++bj)
; #pragma unroll
;                     for (int n = 0; n < 2; ++n) { v[bj][n] = acc[ai][bj][m][n] * rs; const f32x4 q = v[bj][n] * v[bj][n]; ss += (q[0] + q[1]) + (q[2] + q[3]); }
;                 ss = sum_x16_x32(ss);
;                 const float sc = kind < 2 ? __builtin_amdgcn_rsqf(ss * (1.f / 64.f) + RMS_EPS) : 1.f;
;                 const int tt = row & (SEQ - 1); const int prow = (row & ~(SEQ - 1)) + (tt & ((1 << rsh) - 1)) * (SEQ >> rsh) + (tt >> rsh);
; #pragma unroll
;                 for (int bj = 0; bj < 2; ++bj)
;                     gst<u32x4>((kind == 0 ? Oq : Okv + (size_t)(kind - 1) * 16 * M * 64) + ((size_t)(4 * (u.pn & 3) + wc) * M + prow) * 64 + 32 * bj + 8 * fq, pack8(v[bj][0] * sc * gv[bj][0], v[bj][1] * sc * gv[bj][1]));
;             }
.LBB0_186:
	s_waitcnt lgkmcnt(0)
	v_pk_mul_f32 v[94:95], v[94:95], v[100:101] op_sel_hi:[1,0]
	v_pk_mul_f32 v[92:93], v[92:93], v[100:101] op_sel_hi:[1,0]
	v_pk_mul_f32 v[102:103], v[94:95], v[94:95]
	v_pk_mul_f32 v[104:105], v[92:93], v[92:93]
	v_pk_mul_f32 v[86:87], v[86:87], v[100:101] op_sel_hi:[1,0]
	v_pk_mov_b32 v[106:107], v[104:105], v[102:103] op_sel:[1,0]
	v_mov_b32_e32 v105, v103
	v_pk_mul_f32 v[84:85], v[84:85], v[100:101] op_sel_hi:[1,0]
	v_pk_add_f32 v[102:103], v[106:107], v[104:105]
	v_pk_mul_f32 v[104:105], v[86:87], v[86:87]
	v_pk_mul_f32 v[106:107], v[84:85], v[84:85]
	v_pk_mul_f32 v[88:89], v[88:89], v[100:101] op_sel_hi:[1,0]
	v_pk_mov_b32 v[108:109], v[106:107], v[104:105] op_sel:[1,0]
	v_mov_b32_e32 v107, v105
	v_pk_add_f32 v[104:105], v[108:109], v[106:107]
	v_pk_mul_f32 v[108:109], v[88:89], v[88:89]
	v_pk_mul_f32 v[90:91], v[90:91], v[100:101] op_sel_hi:[1,0]
	v_add_f32_e32 v101, v108, v109
	v_pk_mul_f32 v[108:109], v[82:83], v[100:101] op_sel_hi:[1,0]
	v_pk_mul_f32 v[110:111], v[80:81], v[100:101] op_sel_hi:[1,0]
	v_pk_add_f32 v[102:103], v[102:103], v[102:103] op_sel_hi:[0,1]
	v_pk_add_f32 v[104:105], v[104:105], v[104:105] op_sel_hi:[0,1]
	v_pk_mul_f32 v[106:107], v[90:91], v[90:91]
	v_pk_mul_f32 v[80:81], v[108:109], v[108:109]
	v_pk_mul_f32 v[82:83], v[110:111], v[110:111]
	v_add_f32_e32 v107, v106, v107
	v_mov_b32_e32 v100, v82
	v_mov_b32_e32 v106, v83
	v_mov_b32_e32 v102, v80
	v_mov_b32_e32 v104, v81
	v_pk_add_f32 v[82:83], v[100:101], v[106:107]
	v_pk_add_f32 v[80:81], v[102:103], v[104:105]
	v_mov_b32_e32 v115, v96
	v_pk_add_f32 v[80:81], v[82:83], v[80:81]
	s_and_b64 vcc, exec, s[44:45]
	v_add_f32_e32 v80, v80, v81
	v_mov_b32_e32 v81, v80
	s_nop 1
	v_permlane16_swap_b32 v80, v81
	s_nop 1
	s_mov_b64 s[24:25], -1
	v_add_f32_e32 v80, v80, v81
	v_mov_b32_e32 v81, v80
	s_nop 1
	v_permlane32_swap_b32 v80, v81
	s_nop 1
	s_nop 0
	v_add_f32_e32 v80, v80, v81
	v_fmamk_f32 v80, v80, 0x3c800000, v251
	v_rsq_f32_e32 v80, v80
	v_mov_b32_e32 v81, 0x1fef
	v_bitop3_b32 v81, v98, s99, v81 bitop3:0x80
	v_cndmask_b32_e64 v100, 1.0, v80, s[42:43]
	v_and_b32_e32 v80, 0x1fef, v98
	v_lshrrev_b32_e32 v80, s58, v80
	v_or_b32_e32 v80, s26, v80
	v_mad_u32_u24 v80, v81, s59, v80
	v_ashrrev_i32_e32 v81, 31, v80
	v_lshl_add_u64 v[80:81], v[80:81], 0, s[4:5]
	v_lshlrev_b64 v[80:81], 7, v[80:81]
	v_lshl_add_u64 v[80:81], s[0:1], 0, v[80:81]
	v_lshl_add_u64 v[98:99], v[80:81], 0, v[114:115]
	v_pk_mul_f32 v[80:81], v[92:93], v[100:101] op_sel_hi:[1,0]
	v_pk_mul_f32 v[82:83], v[94:95], v[100:101] op_sel_hi:[1,0]
	v_pk_mul_f32 v[80:81], v[144:145], v[80:81]
	v_pk_mul_f32 v[82:83], v[146:147], v[82:83]
	v_pk_mul_f32 v[84:85], v[84:85], v[100:101] op_sel_hi:[1,0]
	v_pk_mul_f32 v[86:87], v[86:87], v[100:101] op_sel_hi:[1,0]
	v_pk_mul_f32 v[84:85], v[142:143], v[84:85]
	v_pk_mul_f32 v[86:87], v[148:149], v[86:87]
	v_cvt_pk_bf16_f32 v80, v80, v81
	v_cvt_pk_bf16_f32 v81, v82, v83
	v_cvt_pk_bf16_f32 v82, v84, v85
	v_pk_mul_f32 v[84:85], v[110:111], v[100:101] op_sel_hi:[1,0]
	v_cvt_pk_bf16_f32 v83, v86, v87
	global_store_dwordx4 v[98:99], v[80:83], off
	v_pk_mul_f32 v[86:87], v[108:109], v[100:101] op_sel_hi:[1,0]
	v_pk_mul_f32 v[84:85], v[150:151], v[84:85]
	v_pk_mul_f32 v[80:81], v[88:89], v[100:101] op_sel_hi:[1,0]
	v_pk_mul_f32 v[82:83], v[90:91], v[100:101] op_sel_hi:[1,0]
	v_pk_mul_f32 v[80:81], v[152:153], v[80:81]
	v_pk_mul_f32 v[82:83], v[154:155], v[82:83]
	v_cvt_pk_bf16_f32 v80, v80, v81
	v_pk_mul_f32 v[86:87], v[156:157], v[86:87]
	v_cvt_pk_bf16_f32 v81, v82, v83
	v_cvt_pk_bf16_f32 v82, v84, v85
	s_nop 0
	v_cvt_pk_bf16_f32 v83, v86, v87
	global_store_dwordx4 v[98:99], v[80:83], off offset:64
	s_cbranch_vccnz .LBB0_188
	s_nop 1
	v_mov_b32_e32 v82, v202
	s_mov_b64 s[24:25], 0

;     __device__ __forceinline__ void operator()(const f32x4 (&acc)[2][2][4][2], const Unit& u, int wr, int wc, int fr, int fq, const LAS float* rt) const {
;     ...
;                 const int row = row0 + ai * 128 + m * 16; const float rs = rt ? rt[wr * 64 + fr + ai * 128 + m * 16] : row_rstd(ssq, row);
;                 f32x4 v[2][2]; float ss = 0.f;
; #pragma unroll
;                 for (int bj = 0; bj < 2; ++bj)
; #pragma unroll
;                     for (int n = 0; n < 2; ++n) { v[bj][n] = acc[ai][bj][m][n] * rs; const f32x4 q = v[bj][n] * v[bj][n]; ss += (q[0] + q[1]) + (q[2] + q[3]); }
;                 ss = sum_x16_x32(ss);
;                 const float sc = kind < 2 ? __builtin_amdgcn_rsqf(ss * (1.f / 64.f) + RMS_EPS) : 1.f;
;                 const int tt = row & (SEQ - 1); const int prow = (row & ~(SEQ - 1)) + (tt & ((1 << rsh) - 1)) * (SEQ >> rsh) + (tt >> rsh);
; #pragma unroll
;                 for (int bj = 0; bj < 2; ++bj)
;                     gst<u32x4>((kind == 0 ? Oq : Okv + (size_t)(kind - 1) * 16 * M * 64) + ((size_t)(4 * (u.pn & 3) + wc) * M + prow) * 64 + 32 * bj + 8 * fq, pack8(v[bj][0] * sc * gv[bj][0], v[bj][1] * sc * gv[bj][1]));
;             }
.LBB0_190:
	s_waitcnt lgkmcnt(0)
	v_pk_mul_f32 v[78:79], v[78:79], v[82:83] op_sel_hi:[1,0]
	v_pk_mul_f32 v[76:77], v[76:77], v[82:83] op_sel_hi:[1,0]
	v_pk_mul_f32 v[84:85], v[78:79], v[78:79]
	v_pk_mul_f32 v[86:87], v[76:77], v[76:77]
	v_pk_mul_f32 v[70:71], v[70:71], v[82:83] op_sel_hi:[1,0]
	v_pk_mov_b32 v[88:89], v[86:87], v[84:85] op_sel:[1,0]
	v_mov_b32_e32 v87, v85
	v_pk_mul_f32 v[68:69], v[68:69], v[82:83] op_sel_hi:[1,0]
	v_pk_add_f32 v[84:85], v[88:89], v[86:87]
	v_pk_mul_f32 v[86:87], v[70:71], v[70:71]
	v_pk_mul_f32 v[88:89], v[68:69], v[68:69]
	v_pk_mul_f32 v[72:73], v[72:73], v[82:83] op_sel_hi:[1,0]
	v_pk_mov_b32 v[90:91], v[88:89], v[86:87] op_sel:[1,0]
	v_mov_b32_e32 v89, v87
	v_pk_add_f32 v[86:87], v[90:91], v[88:89]
	v_pk_mul_f32 v[90:91], v[72:73], v[72:73]
	v_pk_mul_f32 v[74:75], v[74:75], v[82:83] op_sel_hi:[1,0]
	v_add_f32_e32 v83, v90, v91
	v_pk_mul_f32 v[90:91], v[66:67], v[82:83] op_sel_hi:[1,0]
	v_pk_mul_f32 v[92:93], v[64:65], v[82:83] op_sel_hi:[1,0]
	v_pk_add_f32 v[84:85], v[84:85], v[84:85] op_sel_hi:[0,1]
	v_pk_add_f32 v[86:87], v[86:87], v[86:87] op_sel_hi:[0,1]
	v_pk_mul_f32 v[88:89], v[74:75], v[74:75]
	v_pk_mul_f32 v[64:65], v[90:91], v[90:91]
	v_pk_mul_f32 v[66:67], v[92:93], v[92:93]
	v_add_f32_e32 v89, v88, v89
	v_mov_b32_e32 v82, v66
	v_mov_b32_e32 v88, v67
	v_mov_b32_e32 v84, v64
	v_mov_b32_e32 v86, v65
	v_pk_add_f32 v[66:67], v[82:83], v[88:89]
	v_pk_add_f32 v[64:65], v[84:85], v[86:87]
	v_mov_b32_e32 v115, v96
	v_pk_add_f32 v[64:65], v[66:67], v[64:65]
	s_and_b64 vcc, exec, s[44:45]
	v_add_f32_e32 v64, v64, v65
	v_mov_b32_e32 v65, v64
	s_nop 1
	v_permlane16_swap_b32 v64, v65
	s_nop 1
	s_mov_b64 s[24:25], -1
	v_add_f32_e32 v64, v64, v65
	v_mov_b32_e32 v65, v64
	s_nop 1
	v_permlane32_swap_b32 v64, v65
	s_nop 1
	s_nop 0
	v_add_f32_e32 v64, v64, v65
	v_fmamk_f32 v64, v64, 0x3c800000, v251
	v_rsq_f32_e32 v64, v64
	v_mov_b32_e32 v65, 0x1fff
	v_bitop3_b32 v65, v80, s99, v65 bitop3:0x80
	v_cndmask_b32_e64 v82, 1.0, v64, s[42:43]
	v_and_b32_e32 v64, 0x1fff, v80
	v_lshrrev_b32_e32 v64, s58, v64
	v_or_b32_e32 v64, s26, v64
	v_mad_u32_u24 v64, v65, s59, v64
	v_ashrrev_i32_e32 v65, 31, v64
	v_lshl_add_u64 v[64:65], v[64:65], 0, s[4:5]
	v_lshlrev_b64 v[64:65], 7, v[64:65]
	v_lshl_add_u64 v[64:65], s[0:1], 0, v[64:65]
	v_lshl_add_u64 v[80:81], v[64:65], 0, v[114:115]
	v_pk_mul_f32 v[64:65], v[76:77], v[82:83] op_sel_hi:[1,0]
	v_pk_mul_f32 v[66:67], v[78:79], v[82:83] op_sel_hi:[1,0]
	v_pk_mul_f32 v[64:65], v[144:145], v[64:65]
	v_pk_mul_f32 v[66:67], v[146:147], v[66:67]
	v_pk_mul_f32 v[68:69], v[68:69], v[82:83] op_sel_hi:[1,0]
	v_pk_mul_f32 v[70:71], v[70:71], v[82:83] op_sel_hi:[1,0]
	v_pk_mul_f32 v[68:69], v[142:143], v[68:69]
	v_pk_mul_f32 v[70:71], v[148:149], v[70:71]
	v_cvt_pk_bf16_f32 v64, v64, v65
	v_cvt_pk_bf16_f32 v65, v66, v67
	v_cvt_pk_bf16_f32 v66, v68, v69
	v_pk_mul_f32 v[68:69], v[92:93], v[82:83] op_sel_hi:[1,0]
	v_cvt_pk_bf16_f32 v67, v70, v71
	global_store_dwordx4 v[80:81], v[64:67], off
	v_pk_mul_f32 v[70:71], v[90:91], v[82:83] op_sel_hi:[1,0]
	v_pk_mul_f32 v[68:69], v[150:151], v[68:69]
	v_pk_mul_f32 v[64:65], v[72:73], v[82:83] op_sel_hi:[1,0]
	v_pk_mul_f32 v[66:67], v[74:75], v[82:83] op_sel_hi:[1,0]
	v_pk_mul_f32 v[64:65], v[152:153], v[64:65]
	v_pk_mul_f32 v[66:67], v[154:155], v[66:67]
	v_cvt_pk_bf16_f32 v64, v64, v65
	v_pk_mul_f32 v[70:71], v[156:157], v[70:71]
	v_cvt_pk_bf16_f32 v65, v66, v67
	v_cvt_pk_bf16_f32 v66, v68, v69
	s_nop 0
	v_cvt_pk_bf16_f32 v67, v70, v71
	global_store_dwordx4 v[80:81], v[64:67], off offset:64
	s_cbranch_vccnz .LBB0_192
	s_nop 1
	v_mov_b32_e32 v66, v203
	s_mov_b64 s[24:25], 0

;     __device__ __forceinline__ void operator()(const f32x4 (&acc)[2][2][4][2], const Unit& u, int wr, int wc, int fr, int fq, const LAS float* rt) const {
;     ...
;                 const int row = row0 + ai * 128 + m * 16; const float rs = rt ? rt[wr * 64 + fr + ai * 128 + m * 16] : row_rstd(ssq, row);
;                 f32x4 v[2][2]; float ss = 0.f;
; #pragma unroll
;                 for (int bj = 0; bj < 2; ++bj)
; #pragma unroll
;                     for (int n = 0; n < 2; ++n) { v[bj][n] = acc[ai][bj][m][n] * rs; const f32x4 q = v[bj][n] * v[bj][n]; ss += (q[0] + q[1]) + (q[2] + q[3]); }
;                 ss = sum_x16_x32(ss);
;                 const float sc = kind < 2 ? __builtin_amdgcn_rsqf(ss * (1.f / 64.f) + RMS_EPS) : 1.f;
;                 const int tt = row & (SEQ - 1); const int prow = (row & ~(SEQ - 1)) + (tt & ((1 << rsh) - 1)) * (SEQ >> rsh) + (tt >> rsh);
; #pragma unroll
;                 for (int bj = 0; bj < 2; ++bj)
;                     gst<u32x4>((kind == 0 ? Oq : Okv + (size_t)(kind - 1) * 16 * M * 64) + ((size_t)(4 * (u.pn & 3) + wc) * M + prow) * 64 + 32 * bj + 8 * fq, pack8(v[bj][0] * sc * gv[bj][0], v[bj][1] * sc * gv[bj][1]));
;             }
.LBB0_194:
	s_waitcnt lgkmcnt(0)
	v_pk_mul_f32 v[62:63], v[62:63], v[66:67] op_sel_hi:[1,0]
	v_pk_mul_f32 v[60:61], v[60:61], v[66:67] op_sel_hi:[1,0]
	v_pk_mul_f32 v[68:69], v[62:63], v[62:63]
	v_pk_mul_f32 v[70:71], v[60:61], v[60:61]
	v_pk_mul_f32 v[54:55], v[54:55], v[66:67] op_sel_hi:[1,0]
	v_pk_mov_b32 v[72:73], v[70:71], v[68:69] op_sel:[1,0]
	v_mov_b32_e32 v71, v69
	v_pk_mul_f32 v[52:53], v[52:53], v[66:67] op_sel_hi:[1,0]
	v_pk_add_f32 v[68:69], v[72:73], v[70:71]
	v_pk_mul_f32 v[70:71], v[54:55], v[54:55]
	v_pk_mul_f32 v[72:73], v[52:53], v[52:53]
	v_pk_mul_f32 v[56:57], v[56:57], v[66:67] op_sel_hi:[1,0]
	v_pk_mov_b32 v[74:75], v[72:73], v[70:71] op_sel:[1,0]
	v_mov_b32_e32 v73, v71
	v_pk_add_f32 v[70:71], v[74:75], v[72:73]
	v_pk_mul_f32 v[74:75], v[56:57], v[56:57]
	v_pk_mul_f32 v[58:59], v[58:59], v[66:67] op_sel_hi:[1,0]
	v_add_f32_e32 v67, v74, v75
	v_pk_mul_f32 v[74:75], v[50:51], v[66:67] op_sel_hi:[1,0]
	v_pk_mul_f32 v[48:49], v[48:49], v[66:67] op_sel_hi:[1,0]
	v_pk_add_f32 v[68:69], v[68:69], v[68:69] op_sel_hi:[0,1]
	v_pk_add_f32 v[70:71], v[70:71], v[70:71] op_sel_hi:[0,1]
	v_pk_mul_f32 v[72:73], v[58:59], v[58:59]
	v_pk_mul_f32 v[50:51], v[74:75], v[74:75]
	v_pk_mul_f32 v[76:77], v[48:49], v[48:49]
	v_add_f32_e32 v73, v72, v73
	v_mov_b32_e32 v66, v76
	v_mov_b32_e32 v72, v77
	v_mov_b32_e32 v68, v50
	v_mov_b32_e32 v70, v51
	v_pk_add_f32 v[66:67], v[66:67], v[72:73]
	v_pk_add_f32 v[50:51], v[68:69], v[70:71]
	v_and_b32_e32 v65, 0x1fcf, v64
	v_pk_add_f32 v[50:51], v[66:67], v[50:51]
	v_lshrrev_b32_e32 v65, s58, v65
	v_add_f32_e32 v50, v50, v51
	v_mov_b32_e32 v51, v50
	s_nop 1
	v_permlane16_swap_b32 v50, v51
	s_nop 1
	v_bitop3_b32 v66, v64, s99, v252 bitop3:0x80
	v_add_f32_e32 v50, v50, v51
	v_mov_b32_e32 v51, v50
	s_nop 1
	v_permlane32_swap_b32 v50, v51
	s_nop 1
	v_mov_b32_e32 v115, v96
	v_add_f32_e32 v50, v50, v51
	v_fmamk_f32 v50, v50, 0x3c800000, v251
	v_rsq_f32_e32 v50, v50
	v_and_b32_e32 v51, 0xffffe000, v64
	v_or_b32_e32 v65, v65, v51
	v_mad_u32_u24 v66, v66, s59, v65
	v_ashrrev_i32_e32 v67, 31, v66
	v_cndmask_b32_e64 v50, 1.0, v50, s[42:43]
	v_lshl_add_u64 v[66:67], v[66:67], 0, s[4:5]
	v_lshlrev_b64 v[66:67], 7, v[66:67]
	v_pk_mul_f32 v[52:53], v[52:53], v[50:51] op_sel_hi:[1,0]
	v_pk_mul_f32 v[54:55], v[54:55], v[50:51] op_sel_hi:[1,0]
	v_lshl_add_u64 v[66:67], s[0:1], 0, v[66:67]
	v_pk_mul_f32 v[60:61], v[60:61], v[50:51] op_sel_hi:[1,0]
	v_pk_mul_f32 v[62:63], v[62:63], v[50:51] op_sel_hi:[1,0]
	v_pk_mul_f32 v[68:69], v[148:149], v[54:55]
	v_pk_mul_f32 v[54:55], v[142:143], v[52:53]
	v_lshl_add_u64 v[66:67], v[66:67], 0, v[114:115]
	v_pk_mul_f32 v[62:63], v[146:147], v[62:63]
	v_pk_mul_f32 v[60:61], v[144:145], v[60:61]
	v_pk_mul_f32 v[48:49], v[48:49], v[50:51] op_sel_hi:[1,0]
	v_cvt_pk_bf16_f32 v52, v60, v61
	v_cvt_pk_bf16_f32 v53, v62, v63
	v_cvt_pk_bf16_f32 v54, v54, v55
	v_cvt_pk_bf16_f32 v55, v68, v69
	global_store_dwordx4 v[66:67], v[52:55], off
	s_and_b64 vcc, exec, s[44:45]
	s_mov_b64 s[24:25], -1
	v_pk_mul_f32 v[52:53], v[56:57], v[50:51] op_sel_hi:[1,0]
	v_pk_mul_f32 v[54:55], v[58:59], v[50:51] op_sel_hi:[1,0]
	v_pk_mul_f32 v[52:53], v[152:153], v[52:53]
	v_pk_mul_f32 v[54:55], v[154:155], v[54:55]
	v_pk_mul_f32 v[56:57], v[74:75], v[50:51] op_sel_hi:[1,0]
	v_pk_mul_f32 v[48:49], v[150:151], v[48:49]
	v_pk_mul_f32 v[56:57], v[156:157], v[56:57]
	v_cvt_pk_bf16_f32 v52, v52, v53
	v_cvt_pk_bf16_f32 v53, v54, v55
	v_cvt_pk_bf16_f32 v54, v48, v49
	s_nop 0
	v_cvt_pk_bf16_f32 v55, v56, v57
	global_store_dwordx4 v[66:67], v[52:55], off offset:64
	s_cbranch_vccnz .LBB0_196
	s_nop 1
	v_mov_b32_e32 v50, v204
	s_mov_b64 s[24:25], 0

;     __device__ __forceinline__ void operator()(const f32x4 (&acc)[2][2][4][2], const Unit& u, int wr, int wc, int fr, int fq, const LAS float* rt) const {
;     ...
;                 const int row = row0 + ai * 128 + m * 16; const float rs = rt ? rt[wr * 64 + fr + ai * 128 + m * 16] : row_rstd(ssq, row);
;                 f32x4 v[2][2]; float ss = 0.f;
; #pragma unroll
;                 for (int bj = 0; bj < 2; ++bj)
; #pragma unroll
;                     for (int n = 0; n < 2; ++n) { v[bj][n] = acc[ai][bj][m][n] * rs; const f32x4 q = v[bj][n] * v[bj][n]; ss += (q[0] + q[1]) + (q[2] + q[3]); }
;                 ss = sum_x16_x32(ss);
;                 const float sc = kind < 2 ? __builtin_amdgcn_rsqf(ss * (1.f / 64.f) + RMS_EPS) : 1.f;
;                 const int tt = row & (SEQ - 1); const int prow = (row & ~(SEQ - 1)) + (tt & ((1 << rsh) - 1)) * (SEQ >> rsh) + (tt >> rsh);
; #pragma unroll
;                 for (int bj = 0; bj < 2; ++bj)
;                     gst<u32x4>((kind == 0 ? Oq : Okv + (size_t)(kind - 1) * 16 * M * 64) + ((size_t)(4 * (u.pn & 3) + wc) * M + prow) * 64 + 32 * bj + 8 * fq, pack8(v[bj][0] * sc * gv[bj][0], v[bj][1] * sc * gv[bj][1]));
;             }
.LBB0_198:
	s_waitcnt lgkmcnt(0)
	v_pk_mul_f32 v[46:47], v[46:47], v[50:51] op_sel_hi:[1,0]
	v_pk_mul_f32 v[44:45], v[44:45], v[50:51] op_sel_hi:[1,0]
	v_pk_mul_f32 v[52:53], v[46:47], v[46:47]
	v_pk_mul_f32 v[54:55], v[44:45], v[44:45]
	v_pk_mul_f32 v[38:39], v[38:39], v[50:51] op_sel_hi:[1,0]
	v_pk_mov_b32 v[56:57], v[54:55], v[52:53] op_sel:[1,0]
	v_mov_b32_e32 v55, v53
	v_pk_mul_f32 v[36:37], v[36:37], v[50:51] op_sel_hi:[1,0]
	v_pk_add_f32 v[52:53], v[56:57], v[54:55]
	v_pk_mul_f32 v[54:55], v[38:39], v[38:39]
	v_pk_mul_f32 v[56:57], v[36:37], v[36:37]
	v_pk_mul_f32 v[42:43], v[42:43], v[50:51] op_sel_hi:[1,0]
	v_pk_mov_b32 v[58:59], v[56:57], v[54:55] op_sel:[1,0]
	v_mov_b32_e32 v57, v55
	v_pk_add_f32 v[54:55], v[58:59], v[56:57]
	v_pk_mul_f32 v[40:41], v[40:41], v[50:51] op_sel_hi:[1,0]
	v_pk_mul_f32 v[60:61], v[34:35], v[50:51] op_sel_hi:[1,0]
	v_pk_mul_f32 v[62:63], v[32:33], v[50:51] op_sel_hi:[1,0]
	v_pk_add_f32 v[52:53], v[52:53], v[52:53] op_sel_hi:[0,1]
	v_pk_add_f32 v[54:55], v[54:55], v[54:55] op_sel_hi:[0,1]
	v_pk_mul_f32 v[56:57], v[42:43], v[42:43]
	v_pk_mul_f32 v[58:59], v[40:41], v[40:41]
	v_pk_mul_f32 v[32:33], v[60:61], v[60:61]
	v_pk_mul_f32 v[34:35], v[62:63], v[62:63]
	v_add_f32_e32 v59, v58, v59
	v_add_f32_e32 v57, v56, v57
	v_mov_b32_e32 v58, v34
	v_mov_b32_e32 v56, v35
	v_mov_b32_e32 v52, v32
	v_mov_b32_e32 v54, v33
	v_pk_add_f32 v[34:35], v[58:59], v[56:57]
	v_pk_add_f32 v[32:33], v[52:53], v[54:55]
	v_mov_b32_e32 v115, v96
	v_pk_add_f32 v[32:33], v[34:35], v[32:33]
	s_and_b64 vcc, exec, s[44:45]
	v_add_f32_e32 v32, v32, v33
	v_mov_b32_e32 v33, v32
	s_nop 1
	v_permlane16_swap_b32 v33, v32
	s_nop 1
	s_mov_b64 s[24:25], -1
	v_add_f32_e32 v32, v33, v32
	v_mov_b32_e32 v33, v32
	s_nop 1
	v_permlane32_swap_b32 v33, v32
	s_nop 1
	s_nop 0
	v_add_f32_e32 v32, v33, v32
	v_fmamk_f32 v32, v32, 0x3c800000, v251
	v_rsq_f32_e32 v32, v32
	v_mov_b32_e32 v33, 0x1fdf
	v_bitop3_b32 v33, v48, s99, v33 bitop3:0x80
	v_cndmask_b32_e64 v50, 1.0, v32, s[42:43]
	v_and_b32_e32 v32, 0x1fdf, v48
	v_lshrrev_b32_e32 v32, s58, v32
	v_or_b32_e32 v32, v32, v51
	v_mad_u32_u24 v32, v33, s59, v32
	v_ashrrev_i32_e32 v33, 31, v32
	v_lshl_add_u64 v[32:33], v[32:33], 0, s[4:5]
	v_lshlrev_b64 v[32:33], 7, v[32:33]
	v_lshl_add_u64 v[32:33], s[0:1], 0, v[32:33]
	v_lshl_add_u64 v[48:49], v[32:33], 0, v[114:115]
	v_pk_mul_f32 v[32:33], v[44:45], v[50:51] op_sel_hi:[1,0]
	v_pk_mul_f32 v[34:35], v[46:47], v[50:51] op_sel_hi:[1,0]
	v_pk_mul_f32 v[32:33], v[144:145], v[32:33]
	v_pk_mul_f32 v[34:35], v[146:147], v[34:35]
	v_pk_mul_f32 v[36:37], v[36:37], v[50:51] op_sel_hi:[1,0]
	v_pk_mul_f32 v[38:39], v[38:39], v[50:51] op_sel_hi:[1,0]
	v_pk_mul_f32 v[36:37], v[142:143], v[36:37]
	v_pk_mul_f32 v[38:39], v[148:149], v[38:39]
	v_cvt_pk_bf16_f32 v32, v32, v33
	v_cvt_pk_bf16_f32 v33, v34, v35
	v_cvt_pk_bf16_f32 v34, v36, v37
	v_pk_mul_f32 v[36:37], v[62:63], v[50:51] op_sel_hi:[1,0]
	v_cvt_pk_bf16_f32 v35, v38, v39
	global_store_dwordx4 v[48:49], v[32:35], off
	v_pk_mul_f32 v[38:39], v[60:61], v[50:51] op_sel_hi:[1,0]
	v_pk_mul_f32 v[36:37], v[150:151], v[36:37]
	v_pk_mul_f32 v[32:33], v[40:41], v[50:51] op_sel_hi:[1,0]
	v_pk_mul_f32 v[34:35], v[42:43], v[50:51] op_sel_hi:[1,0]
	v_pk_mul_f32 v[32:33], v[152:153], v[32:33]
	v_pk_mul_f32 v[34:35], v[154:155], v[34:35]
	v_cvt_pk_bf16_f32 v32, v32, v33
	v_pk_mul_f32 v[38:39], v[156:157], v[38:39]
	v_cvt_pk_bf16_f32 v33, v34, v35
	v_cvt_pk_bf16_f32 v34, v36, v37
	s_nop 0
	v_cvt_pk_bf16_f32 v35, v38, v39
	global_store_dwordx4 v[48:49], v[32:35], off offset:64
	s_cbranch_vccnz .LBB0_200
	s_nop 1
	v_mov_b32_e32 v34, v205
	s_mov_b64 s[24:25], 0

;     __device__ __forceinline__ void operator()(const f32x4 (&acc)[2][2][4][2], const Unit& u, int wr, int wc, int fr, int fq, const LAS float* rt) const {
;     ...
;                 const int row = row0 + ai * 128 + m * 16; const float rs = rt ? rt[wr * 64 + fr + ai * 128 + m * 16] : row_rstd(ssq, row);
;                 f32x4 v[2][2]; float ss = 0.f;
; #pragma unroll
;                 for (int bj = 0; bj < 2; ++bj)
; #pragma unroll
;                     for (int n = 0; n < 2; ++n) { v[bj][n] = acc[ai][bj][m][n] * rs; const f32x4 q = v[bj][n] * v[bj][n]; ss += (q[0] + q[1]) + (q[2] + q[3]); }
;                 ss = sum_x16_x32(ss);
;                 const float sc = kind < 2 ? __builtin_amdgcn_rsqf(ss * (1.f / 64.f) + RMS_EPS) : 1.f;
;                 const int tt = row & (SEQ - 1); const int prow = (row & ~(SEQ - 1)) + (tt & ((1 << rsh) - 1)) * (SEQ >> rsh) + (tt >> rsh);
; #pragma unroll
;                 for (int bj = 0; bj < 2; ++bj)
;                     gst<u32x4>((kind == 0 ? Oq : Okv + (size_t)(kind - 1) * 16 * M * 64) + ((size_t)(4 * (u.pn & 3) + wc) * M + prow) * 64 + 32 * bj + 8 * fq, pack8(v[bj][0] * sc * gv[bj][0], v[bj][1] * sc * gv[bj][1]));
;             }
.LBB0_202:
	s_waitcnt lgkmcnt(0)
	v_pk_mul_f32 v[30:31], v[30:31], v[34:35] op_sel_hi:[1,0]
	v_pk_mul_f32 v[28:29], v[28:29], v[34:35] op_sel_hi:[1,0]
	v_pk_mul_f32 v[36:37], v[30:31], v[30:31]
	v_pk_mul_f32 v[38:39], v[28:29], v[28:29]
	v_pk_mul_f32 v[22:23], v[22:23], v[34:35] op_sel_hi:[1,0]
	v_pk_mov_b32 v[40:41], v[38:39], v[36:37] op_sel:[1,0]
	v_mov_b32_e32 v39, v37
	v_pk_mul_f32 v[20:21], v[20:21], v[34:35] op_sel_hi:[1,0]
	v_pk_add_f32 v[36:37], v[40:41], v[38:39]
	v_pk_mul_f32 v[38:39], v[22:23], v[22:23]
	v_pk_mul_f32 v[40:41], v[20:21], v[20:21]
	v_pk_mul_f32 v[24:25], v[24:25], v[34:35] op_sel_hi:[1,0]
	v_pk_mov_b32 v[42:43], v[40:41], v[38:39] op_sel:[1,0]
	v_mov_b32_e32 v41, v39
	v_pk_add_f32 v[38:39], v[42:43], v[40:41]
	v_pk_mul_f32 v[42:43], v[24:25], v[24:25]
	v_pk_mul_f32 v[26:27], v[26:27], v[34:35] op_sel_hi:[1,0]
	v_add_f32_e32 v35, v42, v43
	v_pk_mul_f32 v[42:43], v[18:19], v[34:35] op_sel_hi:[1,0]
	v_pk_mul_f32 v[44:45], v[16:17], v[34:35] op_sel_hi:[1,0]
	v_pk_add_f32 v[36:37], v[36:37], v[36:37] op_sel_hi:[0,1]
	v_pk_add_f32 v[38:39], v[38:39], v[38:39] op_sel_hi:[0,1]
	v_pk_mul_f32 v[40:41], v[26:27], v[26:27]
	v_pk_mul_f32 v[16:17], v[42:43], v[42:43]
	v_pk_mul_f32 v[18:19], v[44:45], v[44:45]
	v_add_f32_e32 v41, v40, v41
	v_mov_b32_e32 v34, v18
	v_mov_b32_e32 v40, v19
	v_mov_b32_e32 v36, v16
	v_mov_b32_e32 v38, v17
	v_pk_add_f32 v[18:19], v[34:35], v[40:41]
	v_pk_add_f32 v[16:17], v[36:37], v[38:39]
	v_mov_b32_e32 v115, v96
	v_pk_add_f32 v[16:17], v[18:19], v[16:17]
	s_and_b64 vcc, exec, s[44:45]
	v_add_f32_e32 v16, v16, v17
	v_mov_b32_e32 v17, v16
	s_nop 1
	v_permlane16_swap_b32 v16, v17
	s_nop 1
	s_mov_b64 s[24:25], -1
	v_add_f32_e32 v16, v16, v17
	v_mov_b32_e32 v17, v16
	s_nop 1
	v_permlane32_swap_b32 v16, v17
	s_nop 1
	s_nop 0
	v_add_f32_e32 v16, v16, v17
	v_fmamk_f32 v16, v16, 0x3c800000, v251
	v_rsq_f32_e32 v16, v16
	v_mov_b32_e32 v17, 0x1fef
	v_bitop3_b32 v17, v32, s99, v17 bitop3:0x80
	v_cndmask_b32_e64 v34, 1.0, v16, s[42:43]
	v_and_b32_e32 v16, 0x1fef, v32
	v_lshrrev_b32_e32 v16, s58, v16
	v_or_b32_e32 v16, v16, v51
	v_mad_u32_u24 v16, v17, s59, v16
	v_ashrrev_i32_e32 v17, 31, v16
	v_lshl_add_u64 v[16:17], v[16:17], 0, s[4:5]
	v_lshlrev_b64 v[16:17], 7, v[16:17]
	v_lshl_add_u64 v[16:17], s[0:1], 0, v[16:17]
	v_lshl_add_u64 v[32:33], v[16:17], 0, v[114:115]
	v_pk_mul_f32 v[16:17], v[28:29], v[34:35] op_sel_hi:[1,0]
	v_pk_mul_f32 v[18:19], v[30:31], v[34:35] op_sel_hi:[1,0]
	v_pk_mul_f32 v[16:17], v[144:145], v[16:17]
	v_pk_mul_f32 v[18:19], v[146:147], v[18:19]
	v_pk_mul_f32 v[20:21], v[20:21], v[34:35] op_sel_hi:[1,0]
	v_pk_mul_f32 v[22:23], v[22:23], v[34:35] op_sel_hi:[1,0]
	v_pk_mul_f32 v[20:21], v[142:143], v[20:21]
	v_pk_mul_f32 v[22:23], v[148:149], v[22:23]
	v_cvt_pk_bf16_f32 v16, v16, v17
	v_cvt_pk_bf16_f32 v17, v18, v19
	v_cvt_pk_bf16_f32 v18, v20, v21
	v_pk_mul_f32 v[20:21], v[44:45], v[34:35] op_sel_hi:[1,0]
	v_cvt_pk_bf16_f32 v19, v22, v23
	global_store_dwordx4 v[32:33], v[16:19], off
	v_pk_mul_f32 v[22:23], v[42:43], v[34:35] op_sel_hi:[1,0]
	v_pk_mul_f32 v[20:21], v[150:151], v[20:21]
	v_pk_mul_f32 v[16:17], v[24:25], v[34:35] op_sel_hi:[1,0]
	v_pk_mul_f32 v[18:19], v[26:27], v[34:35] op_sel_hi:[1,0]
	v_pk_mul_f32 v[16:17], v[152:153], v[16:17]
	v_pk_mul_f32 v[18:19], v[154:155], v[18:19]
	v_cvt_pk_bf16_f32 v16, v16, v17
	v_pk_mul_f32 v[22:23], v[156:157], v[22:23]
	v_cvt_pk_bf16_f32 v17, v18, v19
	v_cvt_pk_bf16_f32 v18, v20, v21
	s_nop 0
	v_cvt_pk_bf16_f32 v19, v22, v23
	global_store_dwordx4 v[32:33], v[16:19], off offset:64
	s_cbranch_vccnz .LBB0_204
	s_nop 1
	v_mov_b32_e32 v18, v206
	s_mov_b64 s[24:25], 0

; #define PG8_LAS __attribute__((address_space(3)))
; template <class Epi, class Sched, bool ALIGN_EPI = false, bool SP2 = false>
; __device__ __forceinline__ void gemm_phase(PG8_LAS unsigned char* lds, const Gemm g, const Sched& S, const Epi& E) {
;     ...
;         if constexpr (Epi::RSTD) {
;             const int slot = cur.pm == pmc0 ? 0 : cur.pm == pmc1 ? 1 : cur.pm == pmc2 ? 2 : cur.pm == pmc3 ? 3 : -1;
;             E(acc, cur, wr, wc, fr, fq, slot >= 0 ? (const PG8_LAS float*)(lds + STAGE_BYTES) + slot * 256 : (const PG8_LAS float*)nullptr);
;     __device__ __forceinline__ void operator()(const f32x4 (&acc)[2][2][4][2], const Unit& u, int wr, int wc, int fr, int fq, const LAS float* rt) const {
;     ...
;                 const int row = row0 + ai * 128 + m * 16; const float rs = rt ? rt[wr * 64 + fr + ai * 128 + m * 16] : row_rstd(ssq, row);
.LBB0_255:
	s_cmp_gt_i32 s2, -1
	s_cselect_b64 s[44:45], -1, 0
	s_lshl_b32 s3, s2, 10
	s_add_i32 s3, s3, 0
	s_add_i32 s11, s3, 0x20000
	s_cmp_lt_i32 s2, 0
	s_cselect_b64 s[2:3], -1, 0
	s_and_b64 vcc, s[2:3], exec
	s_cselect_b32 s2, 0, s11
	s_lshl_b32 s3, s57, 2
	v_and_b32_e32 v131, 15, v130
	s_add_i32 s2, s2, s3
	v_lshl_add_u32 v154, v131, 2, s2
	s_mov_b64 s[24:25], -1
	s_cbranch_vccnz .LBB0_257
	ds_read_b32 v150, v154
	ds_read_b32 v200, v154 offset:64
	ds_read_b32 v201, v154 offset:128
	ds_read_b32 v202, v154 offset:192
	ds_read_b32 v203, v154 offset:512
	ds_read_b32 v204, v154 offset:576
	ds_read_b32 v205, v154 offset:640
	ds_read_b32 v206, v154 offset:704
	s_mov_b64 s[24:25], 0

;     __device__ __forceinline__ void operator()(const f32x4 (&acc)[2][2][4][2], const Unit& u, int wr, int wc, int fr, int fq, const LAS float* rt) const {
;     ...
;                 const int row = row0 + ai * 128 + m * 16; const float rs = rt ? rt[wr * 64 + fr + ai * 128 + m * 16] : row_rstd(ssq, row);
;                 if (u.pn < 8) {
;                     const float r2 = rs * rs;
;                     const f32x4 o0 = acc[ai][0][m][0] * acc[ai][1][m][0] * r2, o1 = acc[ai][0][m][1] * acc[ai][1][m][1] * r2;
;                     gst<u32x4>(V + (size_t)row * D + u.pn * 128 + wc * 32 + 8 * fq, pack8(o0, o1));
.LBB0_263:
	s_lshl_b32 s4, s58, 1
	v_lshl_add_u64 v[114:115], v[152:153], 0, s[4:5]
	v_mov_b32_e32 v147, v96
	v_lshl_add_u64 v[114:115], v[114:115], 0, v[146:147]
	global_store_dwordx4 v[114:115], v[130:133], off
	v_cndmask_b32_e64 v114, 0, 1, s[44:45]
	v_cmp_ne_u32_e64 s[42:43], 1, v114
	s_andn2_b64 vcc, exec, s[44:45]
	s_mov_b64 s[44:45], -1
	s_cbranch_vccnz .LBB0_265
	s_nop 1
	v_mov_b32_e32 v120, v200
	s_mov_b64 s[44:45], 0

;     __device__ __forceinline__ void operator()(const f32x4 (&acc)[2][2][4][2], const Unit& u, int wr, int wc, int fr, int fq, const LAS float* rt) const {
;     ...
;                 const int row = row0 + ai * 128 + m * 16; const float rs = rt ? rt[wr * 64 + fr + ai * 128 + m * 16] : row_rstd(ssq, row);
;                 if (u.pn < 8) {
;                     const float r2 = rs * rs;
;                     const f32x4 o0 = acc[ai][0][m][0] * acc[ai][1][m][0] * r2, o1 = acc[ai][0][m][1] * acc[ai][1][m][1] * r2;
;                     gst<u32x4>(V + (size_t)row * D + u.pn * 128 + wc * 32 + 8 * fq, pack8(o0, o1));
.LBB0_271:
	v_lshl_add_u64 v[98:99], v[122:123], 0, s[4:5]
	v_mov_b32_e32 v147, v96
	v_lshl_add_u64 v[98:99], v[98:99], 0, v[146:147]
	s_and_b64 vcc, exec, s[42:43]
	s_mov_b64 s[28:29], -1
	global_store_dwordx4 v[98:99], v[114:117], off
	s_cbranch_vccnz .LBB0_273
	s_nop 1
	v_mov_b32_e32 v104, v201
	v_or_b32_e32 v102, 32, v148
	v_ashrrev_i32_e32 v103, 31, v102
	s_cbranch_execnz .LBB0_275
	s_branch .LBB0_274

;     __device__ __forceinline__ void operator()(const f32x4 (&acc)[2][2][4][2], const Unit& u, int wr, int wc, int fr, int fq, const LAS float* rt) const {
;     ...
;                 const int row = row0 + ai * 128 + m * 16; const float rs = rt ? rt[wr * 64 + fr + ai * 128 + m * 16] : row_rstd(ssq, row);
;                 if (u.pn < 8) {
;                     const float r2 = rs * rs;
;                     const f32x4 o0 = acc[ai][0][m][0] * acc[ai][1][m][0] * r2, o1 = acc[ai][0][m][1] * acc[ai][1][m][1] * r2;
;                     gst<u32x4>(V + (size_t)row * D + u.pn * 128 + wc * 32 + 8 * fq, pack8(o0, o1));
.LBB0_279:
	v_lshl_add_u64 v[80:81], v[106:107], 0, s[4:5]
	v_mov_b32_e32 v147, v96
	v_lshl_add_u64 v[80:81], v[80:81], 0, v[146:147]
	s_and_b64 vcc, exec, s[42:43]
	s_mov_b64 s[28:29], -1
	global_store_dwordx4 v[80:81], v[98:101], off
	s_cbranch_vccnz .LBB0_281
	s_nop 1
	v_mov_b32_e32 v86, v202
	v_or_b32_e32 v84, 48, v148
	v_ashrrev_i32_e32 v85, 31, v84
	s_cbranch_execnz .LBB0_283
	s_branch .LBB0_282

;     __device__ __forceinline__ void operator()(const f32x4 (&acc)[2][2][4][2], const Unit& u, int wr, int wc, int fr, int fq, const LAS float* rt) const {
;     ...
;                 const int row = row0 + ai * 128 + m * 16; const float rs = rt ? rt[wr * 64 + fr + ai * 128 + m * 16] : row_rstd(ssq, row);
;                 if (u.pn < 8) {
;                     const float r2 = rs * rs;
;                     const f32x4 o0 = acc[ai][0][m][0] * acc[ai][1][m][0] * r2, o1 = acc[ai][0][m][1] * acc[ai][1][m][1] * r2;
;                     gst<u32x4>(V + (size_t)row * D + u.pn * 128 + wc * 32 + 8 * fq, pack8(o0, o1));
.LBB0_287:
	v_lshl_add_u64 v[64:65], v[88:89], 0, s[4:5]
	v_mov_b32_e32 v147, v96
	v_lshl_add_u64 v[64:65], v[64:65], 0, v[146:147]
	s_and_b64 vcc, exec, s[42:43]
	s_mov_b64 s[28:29], -1
	global_store_dwordx4 v[64:65], v[80:83], off
	s_cbranch_vccnz .LBB0_289
	s_nop 1
	v_mov_b32_e32 v70, v203
	v_add_u32_e32 v68, 0x80, v148
	v_ashrrev_i32_e32 v69, 31, v68
	s_cbranch_execnz .LBB0_291
	s_branch .LBB0_290

;     __device__ __forceinline__ void operator()(const f32x4 (&acc)[2][2][4][2], const Unit& u, int wr, int wc, int fr, int fq, const LAS float* rt) const {
;     ...
;                 const int row = row0 + ai * 128 + m * 16; const float rs = rt ? rt[wr * 64 + fr + ai * 128 + m * 16] : row_rstd(ssq, row);
;                 if (u.pn < 8) {
;                     const float r2 = rs * rs;
;                     const f32x4 o0 = acc[ai][0][m][0] * acc[ai][1][m][0] * r2, o1 = acc[ai][0][m][1] * acc[ai][1][m][1] * r2;
;                     gst<u32x4>(V + (size_t)row * D + u.pn * 128 + wc * 32 + 8 * fq, pack8(o0, o1));
.LBB0_295:
	v_lshl_add_u64 v[48:49], v[72:73], 0, s[4:5]
	v_mov_b32_e32 v147, v96
	v_lshl_add_u64 v[48:49], v[48:49], 0, v[146:147]
	s_and_b64 vcc, exec, s[42:43]
	s_mov_b64 s[28:29], -1
	global_store_dwordx4 v[48:49], v[64:67], off
	s_cbranch_vccnz .LBB0_297
	s_nop 1
	v_mov_b32_e32 v54, v204
	v_add_u32_e32 v52, 0x90, v148
	v_ashrrev_i32_e32 v53, 31, v52
	s_cbranch_execnz .LBB0_299
	s_branch .LBB0_298

;     __device__ __forceinline__ void operator()(const f32x4 (&acc)[2][2][4][2], const Unit& u, int wr, int wc, int fr, int fq, const LAS float* rt) const {
;     ...
;                 const int row = row0 + ai * 128 + m * 16; const float rs = rt ? rt[wr * 64 + fr + ai * 128 + m * 16] : row_rstd(ssq, row);
;                 if (u.pn < 8) {
;                     const float r2 = rs * rs;
;                     const f32x4 o0 = acc[ai][0][m][0] * acc[ai][1][m][0] * r2, o1 = acc[ai][0][m][1] * acc[ai][1][m][1] * r2;
;                     gst<u32x4>(V + (size_t)row * D + u.pn * 128 + wc * 32 + 8 * fq, pack8(o0, o1));
.LBB0_303:
	v_lshl_add_u64 v[32:33], v[56:57], 0, s[4:5]
	v_mov_b32_e32 v147, v96
	v_lshl_add_u64 v[32:33], v[32:33], 0, v[146:147]
	s_and_b64 vcc, exec, s[42:43]
	s_mov_b64 s[28:29], -1
	global_store_dwordx4 v[32:33], v[48:51], off
	s_cbranch_vccnz .LBB0_305
	s_nop 1
	v_mov_b32_e32 v38, v205
	v_add_u32_e32 v36, 0xa0, v148
	v_ashrrev_i32_e32 v37, 31, v36
	s_cbranch_execnz .LBB0_307
	s_branch .LBB0_306

;     __device__ __forceinline__ void operator()(const f32x4 (&acc)[2][2][4][2], const Unit& u, int wr, int wc, int fr, int fq, const LAS float* rt) const {
;     ...
;                 const int row = row0 + ai * 128 + m * 16; const float rs = rt ? rt[wr * 64 + fr + ai * 128 + m * 16] : row_rstd(ssq, row);
;                 if (u.pn < 8) {
;                     const float r2 = rs * rs;
;                     const f32x4 o0 = acc[ai][0][m][0] * acc[ai][1][m][0] * r2, o1 = acc[ai][0][m][1] * acc[ai][1][m][1] * r2;
;                     gst<u32x4>(V + (size_t)row * D + u.pn * 128 + wc * 32 + 8 * fq, pack8(o0, o1));
.LBB0_311:
	v_lshl_add_u64 v[16:17], v[40:41], 0, s[4:5]
	v_mov_b32_e32 v147, v96
	v_lshl_add_u64 v[16:17], v[16:17], 0, v[146:147]
	s_and_b64 vcc, exec, s[42:43]
	s_mov_b64 s[28:29], -1
	global_store_dwordx4 v[16:17], v[32:35], off
	s_cbranch_vccnz .LBB0_313
	s_nop 1
	v_mov_b32_e32 v22, v206
	v_add_u32_e32 v20, 0xb0, v148
	v_ashrrev_i32_e32 v21, 31, v20
	s_cbranch_execnz .LBB0_315
	s_branch .LBB0_314
